# attention: PV split per q-tile; PV(q-tile 0) MFMAs and V reads interleaved with q-tile 1 softmax VALU (MFMA/VALU co-execution inside the wave), PV(q-tile 1) after
# baseline (speedup 1.0000x reference)
; #define LAS __attribute__((address_space(3)))
; __device__ __forceinline__ unsigned pk2(float lo, float hi) { return pg8::cvt_pk_bf16(lo, hi); }
; __device__ __forceinline__ void attn_unit(const bf16* proj, unsigned char* ws, LAS unsigned char* lds, int a) {
;     ...
;             const float mnew = fmaxf(mrow[rt], mx), alpha = __builtin_amdgcn_exp2f(mrow[rt] - mnew);
;             mrow[rt] = mnew; float ls = lrow[rt] * alpha;
; #pragma unroll
;             for (int dt = 0; dt < 8; ++dt) O[rt][dt] *= alpha;
; #pragma unroll
;             for (int kt = 0; kt < 8; ++kt)
; #pragma unroll
;                 for (int r = 0; r < 4; ++r) { const float p = __builtin_amdgcn_exp2f(st[rt][kt][r] - mnew); st[rt][kt][r] = p; ls += p; }
;             lrow[rt] = ls;
; #pragma unroll
;             for (int tp = 0; tp < 4; ++tp) {
;                 v4u w; w.x = pk2(st[rt][2 * tp][0], st[rt][2 * tp][1]); w.y = pk2(st[rt][2 * tp][2], st[rt][2 * tp][3]);
;                 w.z = pk2(st[rt][2 * tp + 1][0], st[rt][2 * tp + 1][1]); w.w = pk2(st[rt][2 * tp + 1][2], st[rt][2 * tp + 1][3]);
;                 pb[rt][tp] = __builtin_bit_cast(bf16x8, w);
;             }
;         }
; #pragma unroll
;         for (int dt = 0; dt < 8; ++dt)
; #pragma unroll
;             for (int tp = 0; tp < 4; ++tp) {
;                 const LAS unsigned char* p0 = VS + (32 * tp + 4 * fq + (fr >> 2)) * V_STRIDE + (16 * dt + 4 * (fr & 3)) * 2;
;                 const bf16x8 vf = tr_frag(p0, p0 + 16 * V_STRIDE);
;                 O[0][dt] = __builtin_amdgcn_mfma_f32_16x16x32_bf16(vf, pb[0][tp], O[0][dt], 0, 0, 0);
;                 O[1][dt] = __builtin_amdgcn_mfma_f32_16x16x32_bf16(vf, pb[1][tp], O[1][dt], 0, 0, 0);
.LBB0_612:
	v_sub_f32_e32 v209, v209, v207
	v_exp_f32_e32 v210, v209
	s_nop 0
	v_pk_mul_f32 v[66:67], v[66:67], v[210:211] op_sel_hi:[1,0]
	v_pk_mul_f32 v[64:65], v[64:65], v[210:211] op_sel_hi:[1,0]
	v_pk_mul_f32 v[62:63], v[62:63], v[210:211] op_sel_hi:[1,0]
	v_pk_mul_f32 v[60:61], v[60:61], v[210:211] op_sel_hi:[1,0]
	v_pk_mul_f32 v[70:71], v[70:71], v[210:211] op_sel_hi:[1,0]
	v_pk_mul_f32 v[68:69], v[68:69], v[210:211] op_sel_hi:[1,0]
	v_pk_mul_f32 v[74:75], v[74:75], v[210:211] op_sel_hi:[1,0]
	v_pk_mul_f32 v[72:73], v[72:73], v[210:211] op_sel_hi:[1,0]
	v_mul_f32_e64 v78, v78, v210
	v_mul_f32_e64 v79, v79, v210
	v_pk_mul_f32 v[76:77], v[76:77], v[210:211] op_sel_hi:[1,0]
	v_pk_mul_f32 v[82:83], v[82:83], v[210:211] op_sel_hi:[1,0]
	v_pk_mul_f32 v[80:81], v[80:81], v[210:211] op_sel_hi:[1,0]
	v_pk_mul_f32 v[90:91], v[90:91], v[210:211] op_sel_hi:[1,0]
	v_mul_f32_e64 v88, v88, v210
	v_mul_f32_e64 v89, v89, v210
	v_pk_mul_f32 v[98:99], v[98:99], v[210:211] op_sel_hi:[1,0]
	v_pk_mul_f32 v[96:97], v[96:97], v[210:211] op_sel_hi:[1,0]
	s_add_i32 s70, s70, 1
	s_addk_i32 s51, 0x80
	s_and_b64 vcc, exec, s[54:55]
	v_fmac_f32_e32 v238, v179, v210
	v_add_f32_e32 v179, v239, v238
	v_add_f32_e32 v179, v240, v179
	v_add_f32_e32 v179, v241, v179
	v_add_f32_e32 v179, v242, v179
	v_add_f32_e32 v179, v243, v179
	v_add_f32_e32 v179, v244, v179
	v_add_f32_e32 v179, v245, v179
	v_add_f32_e32 v179, v246, v179
	v_add_f32_e32 v179, v247, v179
	v_add_f32_e32 v179, v248, v179
	v_add_f32_e32 v179, v249, v179
	v_add_f32_e32 v179, v250, v179
	v_add_f32_e32 v179, v251, v179
	v_add_f32_e32 v179, v252, v179
	v_add_f32_e32 v179, v253, v179
	ds_read_b64_tr_b16 v[238:239], v202
	ds_read_b64_tr_b16 v[240:241], v202 offset:4608
	ds_read_b64_tr_b16 v[242:243], v202 offset:9216
	ds_read_b64_tr_b16 v[244:245], v202 offset:13824
	ds_read_b64_tr_b16 v[246:247], v202 offset:18432
	ds_read_b64_tr_b16 v[248:249], v202 offset:23040
	v_add_f32_e32 v144, v144, v179
	v_add_f32_e32 v144, v145, v144
	v_add_f32_e32 v144, v146, v144
	v_add_f32_e32 v144, v147, v144
	s_waitcnt lgkmcnt(4)
	v_mfma_f32_16x16x32_bf16 v[64:67], v[238:241], v[108:111], v[64:67]
	ds_read_b64_tr_b16 v[250:251], v202 offset:27648
	ds_read_b64_tr_b16 v[252:253], v202 offset:32256
	v_add_f32_e32 v144, v148, v144
	v_add_f32_e32 v144, v149, v144
	v_add_f32_e32 v144, v150, v144
	v_add_f32_e32 v144, v151, v144
	s_waitcnt lgkmcnt(4)
	v_mfma_f32_16x16x32_bf16 v[64:67], v[242:245], v[104:107], v[64:67]
	ds_read_b64_tr_b16 v[238:239], v202 offset:32
	ds_read_b64_tr_b16 v[240:241], v202 offset:4640
	v_add_f32_e32 v144, v152, v144
	v_add_f32_e32 v144, v153, v144
	v_add_f32_e32 v144, v154, v144
	v_add_f32_e32 v144, v155, v144
	s_waitcnt lgkmcnt(4)
	v_mfma_f32_16x16x32_bf16 v[64:67], v[246:249], v[100:103], v[64:67]
	ds_read_b64_tr_b16 v[242:243], v202 offset:9248
	ds_read_b64_tr_b16 v[244:245], v202 offset:13856
	v_add_f32_e32 v144, v156, v144
	v_add_f32_e32 v144, v157, v144
	v_add_f32_e32 v144, v158, v144
	v_add_f32_e32 v179, v159, v144
	s_waitcnt lgkmcnt(4)
	v_mfma_f32_16x16x32_bf16 v[64:67], v[250:253], v[92:95], v[64:67]
	ds_read_b64_tr_b16 v[246:247], v202 offset:18464
	ds_read_b64_tr_b16 v[248:249], v202 offset:23072
	v_max3_f32 v144, v140, s67, v141
	v_max3_f32 v144, v144, v142, v143
	v_max3_f32 v144, v144, v136, v137
	v_max3_f32 v144, v144, v138, v139
	s_waitcnt lgkmcnt(4)
	v_mfma_f32_16x16x32_bf16 v[60:63], v[238:241], v[108:111], v[60:63]
	ds_read_b64_tr_b16 v[250:251], v202 offset:27680
	ds_read_b64_tr_b16 v[252:253], v202 offset:32288
	v_max3_f32 v144, v144, v132, v133
	v_max3_f32 v144, v144, v134, v135
	v_max3_f32 v144, v144, v128, v129
	v_max3_f32 v144, v144, v130, v131
	s_waitcnt lgkmcnt(4)
	v_mfma_f32_16x16x32_bf16 v[60:63], v[242:245], v[104:107], v[60:63]
	ds_read_b64_tr_b16 v[238:239], v202 offset:64
	ds_read_b64_tr_b16 v[240:241], v202 offset:4672
	v_max3_f32 v144, v144, v124, v125
	v_max3_f32 v144, v144, v126, v127
	v_max3_f32 v144, v144, v120, v121
	v_max3_f32 v144, v144, v122, v123
	s_waitcnt lgkmcnt(4)
	v_mfma_f32_16x16x32_bf16 v[60:63], v[246:249], v[100:103], v[60:63]
	ds_read_b64_tr_b16 v[242:243], v202 offset:9280
	ds_read_b64_tr_b16 v[244:245], v202 offset:13888
	v_max3_f32 v144, v144, v116, v117
	v_max3_f32 v144, v144, v118, v119
	v_max3_f32 v144, v144, v112, v113
	v_max3_f32 v144, v144, v114, v115
	s_waitcnt lgkmcnt(4)
	v_mfma_f32_16x16x32_bf16 v[60:63], v[250:253], v[92:95], v[60:63]
	ds_read_b64_tr_b16 v[246:247], v202 offset:18496
	ds_read_b64_tr_b16 v[248:249], v202 offset:23104
	ds_bpermute_b32 v145, v203, v144
	s_waitcnt lgkmcnt(0)
	v_max_f32_e32 v145, v145, v145
	v_max_f32_e32 v144, v144, v145
	ds_bpermute_b32 v145, v204, v144
	v_mfma_f32_16x16x32_bf16 v[68:71], v[238:241], v[108:111], v[68:71]
	ds_read_b64_tr_b16 v[250:251], v202 offset:27712
	ds_read_b64_tr_b16 v[252:253], v202 offset:32320
	s_waitcnt lgkmcnt(2)
	v_max3_f32 v148, v208, v144, v145
	v_sub_f32_e32 v144, v208, v148
	v_exp_f32_e32 v150, v144
	v_pk_add_f32 v[112:113], v[112:113], v[148:149] op_sel_hi:[1,0] neg_lo:[0,1] neg_hi:[0,1]
	v_mfma_f32_16x16x32_bf16 v[68:71], v[242:245], v[104:107], v[68:71]
	ds_read_b64_tr_b16 v[238:239], v202 offset:96
	ds_read_b64_tr_b16 v[240:241], v202 offset:4704
	v_pk_add_f32 v[114:115], v[114:115], v[148:149] op_sel_hi:[1,0] neg_lo:[0,1] neg_hi:[0,1]
	v_pk_add_f32 v[116:117], v[116:117], v[148:149] op_sel_hi:[1,0] neg_lo:[0,1] neg_hi:[0,1]
	v_pk_add_f32 v[118:119], v[118:119], v[148:149] op_sel_hi:[1,0] neg_lo:[0,1] neg_hi:[0,1]
	v_pk_add_f32 v[120:121], v[120:121], v[148:149] op_sel_hi:[1,0] neg_lo:[0,1] neg_hi:[0,1]
	v_mfma_f32_16x16x32_bf16 v[68:71], v[246:249], v[100:103], v[68:71]
	ds_read_b64_tr_b16 v[242:243], v202 offset:9312
	ds_read_b64_tr_b16 v[244:245], v202 offset:13920
	v_pk_add_f32 v[122:123], v[122:123], v[148:149] op_sel_hi:[1,0] neg_lo:[0,1] neg_hi:[0,1]
	v_pk_add_f32 v[124:125], v[124:125], v[148:149] op_sel_hi:[1,0] neg_lo:[0,1] neg_hi:[0,1]
	v_pk_add_f32 v[126:127], v[126:127], v[148:149] op_sel_hi:[1,0] neg_lo:[0,1] neg_hi:[0,1]
	v_pk_add_f32 v[128:129], v[128:129], v[148:149] op_sel_hi:[1,0] neg_lo:[0,1] neg_hi:[0,1]
	s_waitcnt lgkmcnt(4)
; #define LAS __attribute__((address_space(3)))
; __device__ __forceinline__ void attn_unit(const bf16* proj, unsigned char* ws, LAS unsigned char* lds, int a) {
;     ...
;             const float mnew = fmaxf(mrow[rt], mx), alpha = __builtin_amdgcn_exp2f(mrow[rt] - mnew);
;             mrow[rt] = mnew; float ls = lrow[rt] * alpha;
; #pragma unroll
;             for (int dt = 0; dt < 8; ++dt) O[rt][dt] *= alpha;
; #pragma unroll
;             for (int kt = 0; kt < 8; ++kt)
; #pragma unroll
;                 for (int r = 0; r < 4; ++r) { const float p = __builtin_amdgcn_exp2f(st[rt][kt][r] - mnew); st[rt][kt][r] = p; ls += p; }
;             lrow[rt] = ls;
;     ...
; #pragma unroll
;         for (int dt = 0; dt < 8; ++dt)
; #pragma unroll
;             for (int tp = 0; tp < 4; ++tp) {
;                 const LAS unsigned char* p0 = VS + (32 * tp + 4 * fq + (fr >> 2)) * V_STRIDE + (16 * dt + 4 * (fr & 3)) * 2;
;                 const bf16x8 vf = tr_frag(p0, p0 + 16 * V_STRIDE);
;                 O[0][dt] = __builtin_amdgcn_mfma_f32_16x16x32_bf16(vf, pb[0][tp], O[0][dt], 0, 0, 0);
;                 O[1][dt] = __builtin_amdgcn_mfma_f32_16x16x32_bf16(vf, pb[1][tp], O[1][dt], 0, 0, 0);
	v_mfma_f32_16x16x32_bf16 v[68:71], v[250:253], v[92:95], v[68:71]
	ds_read_b64_tr_b16 v[246:247], v202 offset:18528
	ds_read_b64_tr_b16 v[248:249], v202 offset:23136
	v_pk_add_f32 v[130:131], v[130:131], v[148:149] op_sel_hi:[1,0] neg_lo:[0,1] neg_hi:[0,1]
	v_pk_add_f32 v[132:133], v[132:133], v[148:149] op_sel_hi:[1,0] neg_lo:[0,1] neg_hi:[0,1]
	v_pk_add_f32 v[134:135], v[134:135], v[148:149] op_sel_hi:[1,0] neg_lo:[0,1] neg_hi:[0,1]
	v_pk_add_f32 v[136:137], v[136:137], v[148:149] op_sel_hi:[1,0] neg_lo:[0,1] neg_hi:[0,1]
	s_waitcnt lgkmcnt(4)
	v_mfma_f32_16x16x32_bf16 v[72:75], v[238:241], v[108:111], v[72:75]
	ds_read_b64_tr_b16 v[250:251], v202 offset:27744
	ds_read_b64_tr_b16 v[252:253], v202 offset:32352
	v_pk_add_f32 v[138:139], v[138:139], v[148:149] op_sel_hi:[1,0] neg_lo:[0,1] neg_hi:[0,1]
	v_pk_add_f32 v[140:141], v[140:141], v[148:149] op_sel_hi:[1,0] neg_lo:[0,1] neg_hi:[0,1]
	v_pk_add_f32 v[142:143], v[142:143], v[148:149] op_sel_hi:[1,0] neg_lo:[0,1] neg_hi:[0,1]
	v_exp_f32_e32 v136, v136
	s_waitcnt lgkmcnt(4)
	v_mfma_f32_16x16x32_bf16 v[72:75], v[242:245], v[104:107], v[72:75]
	ds_read_b64_tr_b16 v[238:239], v202 offset:128
	ds_read_b64_tr_b16 v[240:241], v202 offset:4736
	v_pk_mul_f32 v[144:145], v[84:85], v[150:151] op_sel_hi:[1,0]
	v_pk_mul_f32 v[146:147], v[86:87], v[150:151] op_sel_hi:[1,0]
	v_exp_f32_e32 v84, v140
	v_exp_f32_e32 v86, v141
	s_waitcnt lgkmcnt(4)
	v_mfma_f32_16x16x32_bf16 v[72:75], v[246:249], v[100:103], v[72:75]
	ds_read_b64_tr_b16 v[242:243], v202 offset:9344
	ds_read_b64_tr_b16 v[244:245], v202 offset:13952
	v_exp_f32_e32 v87, v142
	v_exp_f32_e32 v140, v143
	v_fma_f32 v85, v176, v150, v84
	v_add_f32_e32 v85, v86, v85
	s_waitcnt lgkmcnt(4)
	v_mfma_f32_16x16x32_bf16 v[72:75], v[250:253], v[92:95], v[72:75]
	ds_read_b64_tr_b16 v[246:247], v202 offset:18560
	ds_read_b64_tr_b16 v[248:249], v202 offset:23168
	v_exp_f32_e32 v137, v137
	v_add_f32_e32 v85, v87, v85
	v_exp_f32_e32 v138, v138
	v_add_f32_e32 v85, v140, v85
	s_waitcnt lgkmcnt(4)
	v_mfma_f32_16x16x32_bf16 v[76:79], v[238:241], v[108:111], v[76:79]
	ds_read_b64_tr_b16 v[250:251], v202 offset:27776
	ds_read_b64_tr_b16 v[252:253], v202 offset:32384
	v_exp_f32_e32 v139, v139
	v_add_f32_e32 v85, v136, v85
	v_exp_f32_e32 v132, v132
	v_add_f32_e32 v85, v137, v85
	s_waitcnt lgkmcnt(4)
	v_mfma_f32_16x16x32_bf16 v[76:79], v[242:245], v[104:107], v[76:79]
	ds_read_b64_tr_b16 v[238:239], v202 offset:160
	ds_read_b64_tr_b16 v[240:241], v202 offset:4768
	v_exp_f32_e32 v133, v133
	v_add_f32_e32 v85, v138, v85
	v_exp_f32_e32 v134, v134
	v_add_f32_e32 v85, v139, v85
	s_waitcnt lgkmcnt(4)
	v_mfma_f32_16x16x32_bf16 v[76:79], v[246:249], v[100:103], v[76:79]
	ds_read_b64_tr_b16 v[242:243], v202 offset:9376
	ds_read_b64_tr_b16 v[244:245], v202 offset:13984
	v_exp_f32_e32 v135, v135
	v_add_f32_e32 v85, v132, v85
	v_exp_f32_e32 v128, v128
	v_add_f32_e32 v85, v133, v85
	s_waitcnt lgkmcnt(4)
	v_mfma_f32_16x16x32_bf16 v[76:79], v[250:253], v[92:95], v[76:79]
	ds_read_b64_tr_b16 v[246:247], v202 offset:18592
	ds_read_b64_tr_b16 v[248:249], v202 offset:23200
	v_exp_f32_e32 v129, v129
	v_add_f32_e32 v85, v134, v85
	v_exp_f32_e32 v130, v130
	v_add_f32_e32 v85, v135, v85
	s_waitcnt lgkmcnt(4)
	v_mfma_f32_16x16x32_bf16 v[80:83], v[238:241], v[108:111], v[80:83]
	ds_read_b64_tr_b16 v[250:251], v202 offset:27808
	ds_read_b64_tr_b16 v[252:253], v202 offset:32416
	v_exp_f32_e32 v131, v131
	v_add_f32_e32 v85, v128, v85
	v_exp_f32_e32 v124, v124
	v_add_f32_e32 v85, v129, v85
	s_waitcnt lgkmcnt(4)
	v_mfma_f32_16x16x32_bf16 v[80:83], v[242:245], v[104:107], v[80:83]
	ds_read_b64_tr_b16 v[238:239], v202 offset:192
	ds_read_b64_tr_b16 v[240:241], v202 offset:4800
	v_exp_f32_e32 v125, v125
	v_add_f32_e32 v85, v130, v85
	v_exp_f32_e32 v126, v126
	v_add_f32_e32 v85, v131, v85
	s_waitcnt lgkmcnt(4)
	v_mfma_f32_16x16x32_bf16 v[80:83], v[246:249], v[100:103], v[80:83]
	ds_read_b64_tr_b16 v[242:243], v202 offset:9408
	ds_read_b64_tr_b16 v[244:245], v202 offset:14016
	v_exp_f32_e32 v127, v127
	v_add_f32_e32 v85, v124, v85
	v_exp_f32_e32 v141, v120
	v_add_f32_e32 v85, v125, v85
	s_waitcnt lgkmcnt(4)
	v_mfma_f32_16x16x32_bf16 v[80:83], v[250:253], v[92:95], v[80:83]
	ds_read_b64_tr_b16 v[246:247], v202 offset:18624
	ds_read_b64_tr_b16 v[248:249], v202 offset:23232
	v_exp_f32_e32 v142, v121
	v_add_f32_e32 v85, v126, v85
	v_exp_f32_e32 v143, v122
	v_add_f32_e32 v85, v127, v85
	s_waitcnt lgkmcnt(4)
	v_mfma_f32_16x16x32_bf16 v[88:91], v[238:241], v[108:111], v[88:91]
	ds_read_b64_tr_b16 v[250:251], v202 offset:27840
	ds_read_b64_tr_b16 v[252:253], v202 offset:32448
	v_exp_f32_e32 v149, v123
	v_pk_mul_f32 v[38:39], v[38:39], v[150:151] op_sel_hi:[1,0]
	v_pk_mul_f32 v[36:37], v[36:37], v[150:151] op_sel_hi:[1,0]
	v_pk_mul_f32 v[34:35], v[34:35], v[150:151] op_sel_hi:[1,0]
	s_waitcnt lgkmcnt(4)
	v_mfma_f32_16x16x32_bf16 v[88:91], v[242:245], v[104:107], v[88:91]
	ds_read_b64_tr_b16 v[238:239], v202 offset:224
	ds_read_b64_tr_b16 v[240:241], v202 offset:4832
	v_pk_mul_f32 v[32:33], v[32:33], v[150:151] op_sel_hi:[1,0]
	v_pk_mul_f32 v[42:43], v[42:43], v[150:151] op_sel_hi:[1,0]
	v_pk_mul_f32 v[40:41], v[40:41], v[150:151] op_sel_hi:[1,0]
	v_pk_mul_f32 v[46:47], v[46:47], v[150:151] op_sel_hi:[1,0]
	s_waitcnt lgkmcnt(4)
	v_mfma_f32_16x16x32_bf16 v[88:91], v[246:249], v[100:103], v[88:91]
	ds_read_b64_tr_b16 v[242:243], v202 offset:9440
	ds_read_b64_tr_b16 v[244:245], v202 offset:14048
	v_pk_mul_f32 v[44:45], v[44:45], v[150:151] op_sel_hi:[1,0]
	v_pk_mul_f32 v[50:51], v[50:51], v[150:151] op_sel_hi:[1,0]
	v_pk_mul_f32 v[48:49], v[48:49], v[150:151] op_sel_hi:[1,0]
	v_pk_mul_f32 v[54:55], v[54:55], v[150:151] op_sel_hi:[1,0]
	s_waitcnt lgkmcnt(4)
; #define LAS __attribute__((address_space(3)))
; __device__ __forceinline__ unsigned pk2(float lo, float hi) { return pg8::cvt_pk_bf16(lo, hi); }
; __device__ __forceinline__ void attn_unit(const bf16* proj, unsigned char* ws, LAS unsigned char* lds, int a) {
;     ...
; #pragma unroll
;                 for (int r = 0; r < 4; ++r) { const float p = __builtin_amdgcn_exp2f(st[rt][kt][r] - mnew); st[rt][kt][r] = p; ls += p; }
;             lrow[rt] = ls;
; #pragma unroll
;             for (int tp = 0; tp < 4; ++tp) {
;                 v4u w; w.x = pk2(st[rt][2 * tp][0], st[rt][2 * tp][1]); w.y = pk2(st[rt][2 * tp][2], st[rt][2 * tp][3]);
;                 w.z = pk2(st[rt][2 * tp + 1][0], st[rt][2 * tp + 1][1]); w.w = pk2(st[rt][2 * tp + 1][2], st[rt][2 * tp + 1][3]);
;                 pb[rt][tp] = __builtin_bit_cast(bf16x8, w);
;             }
;         }
; #pragma unroll
;         for (int dt = 0; dt < 8; ++dt)
; #pragma unroll
;             for (int tp = 0; tp < 4; ++tp) {
;                 const LAS unsigned char* p0 = VS + (32 * tp + 4 * fq + (fr >> 2)) * V_STRIDE + (16 * dt + 4 * (fr & 3)) * 2;
;                 const bf16x8 vf = tr_frag(p0, p0 + 16 * V_STRIDE);
;                 O[0][dt] = __builtin_amdgcn_mfma_f32_16x16x32_bf16(vf, pb[0][tp], O[0][dt], 0, 0, 0);
;                 O[1][dt] = __builtin_amdgcn_mfma_f32_16x16x32_bf16(vf, pb[1][tp], O[1][dt], 0, 0, 0);
	v_mfma_f32_16x16x32_bf16 v[88:91], v[250:253], v[92:95], v[88:91]
	ds_read_b64_tr_b16 v[246:247], v202 offset:18656
	ds_read_b64_tr_b16 v[248:249], v202 offset:23264
	v_pk_mul_f32 v[52:53], v[52:53], v[150:151] op_sel_hi:[1,0]
	v_pk_mul_f32 v[58:59], v[58:59], v[150:151] op_sel_hi:[1,0]
	v_pk_mul_f32 v[56:57], v[56:57], v[150:151] op_sel_hi:[1,0]
	v_add_f32_e32 v85, v141, v85
	s_waitcnt lgkmcnt(4)
	v_mfma_f32_16x16x32_bf16 v[96:99], v[238:241], v[108:111], v[96:99]
	ds_read_b64_tr_b16 v[250:251], v202 offset:27872
	ds_read_b64_tr_b16 v[252:253], v202 offset:32480
	v_exp_f32_e32 v150, v116
	v_add_f32_e32 v85, v142, v85
	v_exp_f32_e32 v151, v117
	v_add_f32_e32 v85, v143, v85
	s_waitcnt lgkmcnt(4)
	v_mfma_f32_16x16x32_bf16 v[96:99], v[242:245], v[104:107], v[96:99]
	v_exp_f32_e32 v152, v118
	v_add_f32_e32 v85, v149, v85
	v_exp_f32_e32 v153, v119
	v_add_f32_e32 v85, v150, v85
	s_waitcnt lgkmcnt(2)
	v_mfma_f32_16x16x32_bf16 v[96:99], v[246:249], v[100:103], v[96:99]
	v_exp_f32_e32 v154, v112
	v_add_f32_e32 v85, v151, v85
	v_exp_f32_e32 v155, v113
	v_add_f32_e32 v85, v152, v85
	s_waitcnt lgkmcnt(0)
	v_mfma_f32_16x16x32_bf16 v[96:99], v[250:253], v[92:95], v[96:99]
	v_exp_f32_e32 v156, v114
	v_add_f32_e32 v85, v153, v85
	v_exp_f32_e32 v157, v115
	v_add_f32_e32 v85, v154, v85
	v_add_f32_e32 v85, v155, v85
	v_add_f32_e32 v85, v156, v85
	v_add_f32_e32 v176, v157, v85
	v_cvt_pk_bf16_f32 v120, v84, v86
	v_cvt_pk_bf16_f32 v121, v87, v140
	v_cvt_pk_bf16_f32 v122, v136, v137
	v_cvt_pk_bf16_f32 v123, v138, v139
	v_cvt_pk_bf16_f32 v116, v132, v133
	v_cvt_pk_bf16_f32 v117, v134, v135
	v_cvt_pk_bf16_f32 v118, v128, v129
	v_cvt_pk_bf16_f32 v119, v130, v131
	v_cvt_pk_bf16_f32 v112, v124, v125
	v_cvt_pk_bf16_f32 v113, v126, v127
	v_cvt_pk_bf16_f32 v114, v141, v142
	v_cvt_pk_bf16_f32 v115, v143, v149
	v_cvt_pk_bf16_f32 v84, v150, v151
	v_cvt_pk_bf16_f32 v85, v152, v153
	v_cvt_pk_bf16_f32 v86, v154, v155
	v_cvt_pk_bf16_f32 v87, v156, v157
	ds_read_b64_tr_b16 v[124:125], v202
	ds_read_b64_tr_b16 v[126:127], v202 offset:4608
	ds_read_b64_tr_b16 v[128:129], v202 offset:9216
	ds_read_b64_tr_b16 v[130:131], v202 offset:13824
	ds_read_b64_tr_b16 v[132:133], v202 offset:18432
	ds_read_b64_tr_b16 v[134:135], v202 offset:23040
	s_waitcnt lgkmcnt(4)
	v_mfma_f32_16x16x32_bf16 v[36:39], v[124:127], v[120:123], v[36:39]
	ds_read_b64_tr_b16 v[136:137], v202 offset:27648
	ds_read_b64_tr_b16 v[138:139], v202 offset:32256
	s_waitcnt lgkmcnt(4)
	v_mfma_f32_16x16x32_bf16 v[36:39], v[128:131], v[116:119], v[36:39]
	ds_read_b64_tr_b16 v[124:125], v202 offset:32
	ds_read_b64_tr_b16 v[126:127], v202 offset:4640
	s_waitcnt lgkmcnt(4)
	v_mfma_f32_16x16x32_bf16 v[36:39], v[132:135], v[112:115], v[36:39]
	ds_read_b64_tr_b16 v[128:129], v202 offset:9248
	ds_read_b64_tr_b16 v[130:131], v202 offset:13856
	s_waitcnt lgkmcnt(4)
	v_mfma_f32_16x16x32_bf16 v[36:39], v[136:139], v[84:87], v[36:39]
	ds_read_b64_tr_b16 v[132:133], v202 offset:18464
	ds_read_b64_tr_b16 v[134:135], v202 offset:23072
	s_waitcnt lgkmcnt(4)
	v_mfma_f32_16x16x32_bf16 v[32:35], v[124:127], v[120:123], v[32:35]
	ds_read_b64_tr_b16 v[136:137], v202 offset:27680
	ds_read_b64_tr_b16 v[138:139], v202 offset:32288
	s_waitcnt lgkmcnt(4)
	v_mfma_f32_16x16x32_bf16 v[32:35], v[128:131], v[116:119], v[32:35]
	ds_read_b64_tr_b16 v[124:125], v202 offset:64
	ds_read_b64_tr_b16 v[126:127], v202 offset:4672
	s_waitcnt lgkmcnt(4)
	v_mfma_f32_16x16x32_bf16 v[32:35], v[132:135], v[112:115], v[32:35]
	ds_read_b64_tr_b16 v[128:129], v202 offset:9280
	ds_read_b64_tr_b16 v[130:131], v202 offset:13888
	s_waitcnt lgkmcnt(4)
	v_mfma_f32_16x16x32_bf16 v[32:35], v[136:139], v[84:87], v[32:35]
	ds_read_b64_tr_b16 v[132:133], v202 offset:18496
	ds_read_b64_tr_b16 v[134:135], v202 offset:23104
	s_waitcnt lgkmcnt(4)
	v_mfma_f32_16x16x32_bf16 v[40:43], v[124:127], v[120:123], v[40:43]
	ds_read_b64_tr_b16 v[136:137], v202 offset:27712
	ds_read_b64_tr_b16 v[138:139], v202 offset:32320
	s_waitcnt lgkmcnt(4)
	v_mfma_f32_16x16x32_bf16 v[40:43], v[128:131], v[116:119], v[40:43]
	ds_read_b64_tr_b16 v[124:125], v202 offset:96
	ds_read_b64_tr_b16 v[126:127], v202 offset:4704
	s_waitcnt lgkmcnt(4)
; #define LAS __attribute__((address_space(3)))
; __device__ __forceinline__ void attn_unit(const bf16* proj, unsigned char* ws, LAS unsigned char* lds, int a) {
;     ...
; #pragma unroll
;         for (int dt = 0; dt < 8; ++dt)
; #pragma unroll
;             for (int tp = 0; tp < 4; ++tp) {
;                 const LAS unsigned char* p0 = VS + (32 * tp + 4 * fq + (fr >> 2)) * V_STRIDE + (16 * dt + 4 * (fr & 3)) * 2;
;                 const bf16x8 vf = tr_frag(p0, p0 + 16 * V_STRIDE);
;                 O[0][dt] = __builtin_amdgcn_mfma_f32_16x16x32_bf16(vf, pb[0][tp], O[0][dt], 0, 0, 0);
;                 O[1][dt] = __builtin_amdgcn_mfma_f32_16x16x32_bf16(vf, pb[1][tp], O[1][dt], 0, 0, 0);
;             }
	v_mfma_f32_16x16x32_bf16 v[40:43], v[132:135], v[112:115], v[40:43]
	ds_read_b64_tr_b16 v[128:129], v202 offset:9312
	ds_read_b64_tr_b16 v[130:131], v202 offset:13920
	s_waitcnt lgkmcnt(4)
	v_mfma_f32_16x16x32_bf16 v[40:43], v[136:139], v[84:87], v[40:43]
	ds_read_b64_tr_b16 v[132:133], v202 offset:18528
	ds_read_b64_tr_b16 v[134:135], v202 offset:23136
	s_waitcnt lgkmcnt(4)
	v_mfma_f32_16x16x32_bf16 v[44:47], v[124:127], v[120:123], v[44:47]
	ds_read_b64_tr_b16 v[136:137], v202 offset:27744
	ds_read_b64_tr_b16 v[138:139], v202 offset:32352
	s_waitcnt lgkmcnt(4)
	v_mfma_f32_16x16x32_bf16 v[44:47], v[128:131], v[116:119], v[44:47]
	ds_read_b64_tr_b16 v[124:125], v202 offset:128
	ds_read_b64_tr_b16 v[126:127], v202 offset:4736
	s_waitcnt lgkmcnt(4)
	v_mfma_f32_16x16x32_bf16 v[44:47], v[132:135], v[112:115], v[44:47]
	ds_read_b64_tr_b16 v[128:129], v202 offset:9344
	ds_read_b64_tr_b16 v[130:131], v202 offset:13952
	s_waitcnt lgkmcnt(4)
	v_mfma_f32_16x16x32_bf16 v[44:47], v[136:139], v[84:87], v[44:47]
	ds_read_b64_tr_b16 v[132:133], v202 offset:18560
	ds_read_b64_tr_b16 v[134:135], v202 offset:23168
	s_waitcnt lgkmcnt(4)
	v_mfma_f32_16x16x32_bf16 v[48:51], v[124:127], v[120:123], v[48:51]
	ds_read_b64_tr_b16 v[136:137], v202 offset:27776
	ds_read_b64_tr_b16 v[138:139], v202 offset:32384
	s_waitcnt lgkmcnt(4)
	v_mfma_f32_16x16x32_bf16 v[48:51], v[128:131], v[116:119], v[48:51]
	ds_read_b64_tr_b16 v[124:125], v202 offset:160
	ds_read_b64_tr_b16 v[126:127], v202 offset:4768
	s_waitcnt lgkmcnt(4)
	v_mfma_f32_16x16x32_bf16 v[48:51], v[132:135], v[112:115], v[48:51]
	ds_read_b64_tr_b16 v[128:129], v202 offset:9376
	ds_read_b64_tr_b16 v[130:131], v202 offset:13984
	s_waitcnt lgkmcnt(4)
	v_mfma_f32_16x16x32_bf16 v[48:51], v[136:139], v[84:87], v[48:51]
	ds_read_b64_tr_b16 v[132:133], v202 offset:18592
	ds_read_b64_tr_b16 v[134:135], v202 offset:23200
	s_waitcnt lgkmcnt(4)
	v_mfma_f32_16x16x32_bf16 v[52:55], v[124:127], v[120:123], v[52:55]
	ds_read_b64_tr_b16 v[136:137], v202 offset:27808
	ds_read_b64_tr_b16 v[138:139], v202 offset:32416
	s_waitcnt lgkmcnt(4)
	v_mfma_f32_16x16x32_bf16 v[52:55], v[128:131], v[116:119], v[52:55]
	ds_read_b64_tr_b16 v[124:125], v202 offset:192
	ds_read_b64_tr_b16 v[126:127], v202 offset:4800
	s_waitcnt lgkmcnt(4)
	v_mfma_f32_16x16x32_bf16 v[52:55], v[132:135], v[112:115], v[52:55]
	ds_read_b64_tr_b16 v[128:129], v202 offset:9408
	ds_read_b64_tr_b16 v[130:131], v202 offset:14016
	s_waitcnt lgkmcnt(4)
	v_mfma_f32_16x16x32_bf16 v[52:55], v[136:139], v[84:87], v[52:55]
	ds_read_b64_tr_b16 v[132:133], v202 offset:18624
	ds_read_b64_tr_b16 v[134:135], v202 offset:23232
	s_waitcnt lgkmcnt(4)
	v_mfma_f32_16x16x32_bf16 v[56:59], v[124:127], v[120:123], v[56:59]
	ds_read_b64_tr_b16 v[136:137], v202 offset:27840
	ds_read_b64_tr_b16 v[138:139], v202 offset:32448
	s_waitcnt lgkmcnt(4)
	v_mfma_f32_16x16x32_bf16 v[56:59], v[128:131], v[116:119], v[56:59]
	ds_read_b64_tr_b16 v[124:125], v202 offset:224
	ds_read_b64_tr_b16 v[126:127], v202 offset:4832
	s_waitcnt lgkmcnt(4)
	v_mfma_f32_16x16x32_bf16 v[56:59], v[132:135], v[112:115], v[56:59]
	ds_read_b64_tr_b16 v[128:129], v202 offset:9440
	ds_read_b64_tr_b16 v[130:131], v202 offset:14048
	s_waitcnt lgkmcnt(4)
	v_mfma_f32_16x16x32_bf16 v[56:59], v[136:139], v[84:87], v[56:59]
	ds_read_b64_tr_b16 v[132:133], v202 offset:18656
	ds_read_b64_tr_b16 v[134:135], v202 offset:23264
	s_waitcnt lgkmcnt(4)
	v_mfma_f32_16x16x32_bf16 v[108:111], v[124:127], v[120:123], v[144:147]
	ds_read_b64_tr_b16 v[136:137], v202 offset:27872
	ds_read_b64_tr_b16 v[138:139], v202 offset:32480
	s_waitcnt lgkmcnt(4)
	v_mfma_f32_16x16x32_bf16 v[104:107], v[128:131], v[116:119], v[108:111]
	s_waitcnt lgkmcnt(2)
	v_mfma_f32_16x16x32_bf16 v[100:103], v[132:135], v[112:115], v[104:107]
	s_waitcnt lgkmcnt(0)
	v_mfma_f32_16x16x32_bf16 v[84:87], v[136:139], v[84:87], v[100:103]
	s_cbranch_vccnz .LBB0_614
	v_mov_b32_e32 v209, v207
	v_mov_b32_e32 v208, v148
	s_cmp_eq_u32 s51, 0
	s_cbranch_scc0 .LBB0_605
	s_branch .LBB0_606
